# P4 EpiGlu epilogue hand-written: 16 Z loads up front as 16B/lane via permlane16_swap, sigmoids under load latency, 16B ZO stores
# speedup vs baseline: 1.0035x; 1.0035x over previous
.LBB0_1061:
	s_sext_i32_i8 s24, s44
	v_lshl_add_u32 v138, s45, 8, v140
	v_lshl_or_b32 v136, s24, 8, v142
	v_bfe_u32 v137, v142, 2, 1
	v_mul_u32_u24_e32 v137, 12, v137
	v_add_u32_e32 v136, v136, v137
	v_lshlrev_b32_e32 v139, 1, v136
	v_lshl_add_u32 v146, v138, 11, v139
	v_lshl_add_u32 v147, v138, 12, v139
	v_mov_b32_e32 v212, v146
	v_mov_b32_e32 v220, v147
	v_add_u32_e32 v213, 0x8000, v146
	v_add_u32_e32 v221, 0x10000, v147
	v_add_u32_e32 v214, 0x10000, v146
	v_add_u32_e32 v222, 0x20000, v147
	v_add_u32_e32 v215, 0x18000, v146
	v_add_u32_e32 v223, 0x30000, v147
	v_add_u32_e32 v216, 0x40000, v146
	v_add_u32_e32 v224, 0x80000, v147
	v_add_u32_e32 v217, 0x48000, v146
	v_add_u32_e32 v225, 0x90000, v147
	v_add_u32_e32 v218, 0x50000, v146
	v_add_u32_e32 v226, 0xa0000, v147
	v_add_u32_e32 v219, 0x58000, v146
	v_add_u32_e32 v227, 0xb0000, v147
	global_load_dwordx4 v[148:151], v212, s[6:7] offset:0
	global_load_dwordx4 v[152:155], v212, s[6:7] offset:256
	global_load_dwordx4 v[156:159], v213, s[6:7] offset:0
	global_load_dwordx4 v[160:163], v213, s[6:7] offset:256
	global_load_dwordx4 v[164:167], v214, s[6:7] offset:0
	global_load_dwordx4 v[168:171], v214, s[6:7] offset:256
	global_load_dwordx4 v[172:175], v215, s[6:7] offset:0
	global_load_dwordx4 v[176:179], v215, s[6:7] offset:256
	global_load_dwordx4 v[180:183], v216, s[6:7] offset:0
	global_load_dwordx4 v[184:187], v216, s[6:7] offset:256
	global_load_dwordx4 v[188:191], v217, s[6:7] offset:0
	global_load_dwordx4 v[192:195], v217, s[6:7] offset:256
	global_load_dwordx4 v[196:199], v218, s[6:7] offset:0
	global_load_dwordx4 v[200:203], v218, s[6:7] offset:256
	global_load_dwordx4 v[204:207], v219, s[6:7] offset:0
	global_load_dwordx4 v[208:211], v219, s[6:7] offset:256
	v_mul_f32_e32 v124, 0xbfb8aa3b, v124
	v_mul_f32_e32 v125, 0xbfb8aa3b, v125
	v_mul_f32_e32 v126, 0xbfb8aa3b, v126
	v_mul_f32_e32 v127, 0xbfb8aa3b, v127
	v_exp_f32_e32 v124, v124
	v_exp_f32_e32 v125, v125
	v_exp_f32_e32 v126, v126
	v_exp_f32_e32 v127, v127
	v_add_f32_e32 v124, 1.0, v124
	v_add_f32_e32 v125, 1.0, v125
	v_add_f32_e32 v126, 1.0, v126
	v_add_f32_e32 v127, 1.0, v127
	v_rcp_f32_e32 v124, v124
	v_rcp_f32_e32 v125, v125
	v_rcp_f32_e32 v126, v126
	v_rcp_f32_e32 v127, v127
	v_mul_f32_e32 v120, 0xbfb8aa3b, v120
	v_mul_f32_e32 v121, 0xbfb8aa3b, v121
	v_mul_f32_e32 v122, 0xbfb8aa3b, v122
	v_mul_f32_e32 v123, 0xbfb8aa3b, v123
	v_exp_f32_e32 v120, v120
	v_exp_f32_e32 v121, v121
	v_exp_f32_e32 v122, v122
	v_exp_f32_e32 v123, v123
	v_add_f32_e32 v120, 1.0, v120
	v_add_f32_e32 v121, 1.0, v121
	v_add_f32_e32 v122, 1.0, v122
	v_add_f32_e32 v123, 1.0, v123
	v_rcp_f32_e32 v120, v120
	v_rcp_f32_e32 v121, v121
	v_rcp_f32_e32 v122, v122
	v_rcp_f32_e32 v123, v123
	v_mul_f32_e32 v108, 0xbfb8aa3b, v108
	v_mul_f32_e32 v109, 0xbfb8aa3b, v109
	v_mul_f32_e32 v110, 0xbfb8aa3b, v110
	v_mul_f32_e32 v111, 0xbfb8aa3b, v111
	v_exp_f32_e32 v108, v108
	v_exp_f32_e32 v109, v109
	v_exp_f32_e32 v110, v110
	v_exp_f32_e32 v111, v111
	v_add_f32_e32 v108, 1.0, v108
	v_add_f32_e32 v109, 1.0, v109
	v_add_f32_e32 v110, 1.0, v110
	v_add_f32_e32 v111, 1.0, v111
	v_rcp_f32_e32 v108, v108
	v_rcp_f32_e32 v109, v109
	v_rcp_f32_e32 v110, v110
	v_rcp_f32_e32 v111, v111
	v_mul_f32_e32 v104, 0xbfb8aa3b, v104
	v_mul_f32_e32 v105, 0xbfb8aa3b, v105
	v_mul_f32_e32 v106, 0xbfb8aa3b, v106
	v_mul_f32_e32 v107, 0xbfb8aa3b, v107
	v_exp_f32_e32 v104, v104
	v_exp_f32_e32 v105, v105
	v_exp_f32_e32 v106, v106
	v_exp_f32_e32 v107, v107
	v_add_f32_e32 v104, 1.0, v104
	v_add_f32_e32 v105, 1.0, v105
	v_add_f32_e32 v106, 1.0, v106
	v_add_f32_e32 v107, 1.0, v107
	v_rcp_f32_e32 v104, v104
	v_rcp_f32_e32 v105, v105
	v_rcp_f32_e32 v106, v106
	v_rcp_f32_e32 v107, v107
	v_mul_f32_e32 v92, 0xbfb8aa3b, v92
	v_mul_f32_e32 v93, 0xbfb8aa3b, v93
	v_mul_f32_e32 v94, 0xbfb8aa3b, v94
	v_mul_f32_e32 v95, 0xbfb8aa3b, v95
	v_exp_f32_e32 v92, v92
	v_exp_f32_e32 v93, v93
	v_exp_f32_e32 v94, v94
	v_exp_f32_e32 v95, v95
	v_add_f32_e32 v92, 1.0, v92
	v_add_f32_e32 v93, 1.0, v93
	v_add_f32_e32 v94, 1.0, v94
	v_add_f32_e32 v95, 1.0, v95
	v_rcp_f32_e32 v92, v92
	v_rcp_f32_e32 v93, v93
	v_rcp_f32_e32 v94, v94
	v_rcp_f32_e32 v95, v95
	v_mul_f32_e32 v88, 0xbfb8aa3b, v88
	v_mul_f32_e32 v89, 0xbfb8aa3b, v89
	v_mul_f32_e32 v90, 0xbfb8aa3b, v90
	v_mul_f32_e32 v91, 0xbfb8aa3b, v91
	v_exp_f32_e32 v88, v88
	v_exp_f32_e32 v89, v89
	v_exp_f32_e32 v90, v90
	v_exp_f32_e32 v91, v91
	v_add_f32_e32 v88, 1.0, v88
	v_add_f32_e32 v89, 1.0, v89
	v_add_f32_e32 v90, 1.0, v90
	v_add_f32_e32 v91, 1.0, v91
	v_rcp_f32_e32 v88, v88
	v_rcp_f32_e32 v89, v89
	v_rcp_f32_e32 v90, v90
	v_rcp_f32_e32 v91, v91
	v_mul_f32_e32 v76, 0xbfb8aa3b, v76
	v_mul_f32_e32 v77, 0xbfb8aa3b, v77
	v_mul_f32_e32 v78, 0xbfb8aa3b, v78
	v_mul_f32_e32 v79, 0xbfb8aa3b, v79
	v_exp_f32_e32 v76, v76
	v_exp_f32_e32 v77, v77
	v_exp_f32_e32 v78, v78
	v_exp_f32_e32 v79, v79
	v_add_f32_e32 v76, 1.0, v76
	v_add_f32_e32 v77, 1.0, v77
	v_add_f32_e32 v78, 1.0, v78
	v_add_f32_e32 v79, 1.0, v79
	v_rcp_f32_e32 v76, v76
	v_rcp_f32_e32 v77, v77
	v_rcp_f32_e32 v78, v78
	v_rcp_f32_e32 v79, v79
	v_mul_f32_e32 v72, 0xbfb8aa3b, v72
	v_mul_f32_e32 v73, 0xbfb8aa3b, v73
	v_mul_f32_e32 v74, 0xbfb8aa3b, v74
	v_mul_f32_e32 v75, 0xbfb8aa3b, v75
	v_exp_f32_e32 v72, v72
	v_exp_f32_e32 v73, v73
	v_exp_f32_e32 v74, v74
	v_exp_f32_e32 v75, v75
	v_add_f32_e32 v72, 1.0, v72
	v_add_f32_e32 v73, 1.0, v73
	v_add_f32_e32 v74, 1.0, v74
	v_add_f32_e32 v75, 1.0, v75
	v_rcp_f32_e32 v72, v72
	v_rcp_f32_e32 v73, v73
	v_rcp_f32_e32 v74, v74
	v_rcp_f32_e32 v75, v75
	v_mul_f32_e32 v116, 0xbfb8aa3b, v116
	v_mul_f32_e32 v117, 0xbfb8aa3b, v117
	v_mul_f32_e32 v118, 0xbfb8aa3b, v118
	v_mul_f32_e32 v119, 0xbfb8aa3b, v119
	v_exp_f32_e32 v116, v116
	v_exp_f32_e32 v117, v117
	v_exp_f32_e32 v118, v118
	v_exp_f32_e32 v119, v119
	v_add_f32_e32 v116, 1.0, v116
	v_add_f32_e32 v117, 1.0, v117
	v_add_f32_e32 v118, 1.0, v118
	v_add_f32_e32 v119, 1.0, v119
	v_rcp_f32_e32 v116, v116
	v_rcp_f32_e32 v117, v117
	v_rcp_f32_e32 v118, v118
	v_rcp_f32_e32 v119, v119
	v_mul_f32_e32 v112, 0xbfb8aa3b, v112
	v_mul_f32_e32 v113, 0xbfb8aa3b, v113
	v_mul_f32_e32 v114, 0xbfb8aa3b, v114
	v_mul_f32_e32 v115, 0xbfb8aa3b, v115
	v_exp_f32_e32 v112, v112
	v_exp_f32_e32 v113, v113
	v_exp_f32_e32 v114, v114
	v_exp_f32_e32 v115, v115
	v_add_f32_e32 v112, 1.0, v112
	v_add_f32_e32 v113, 1.0, v113
	v_add_f32_e32 v114, 1.0, v114
	v_add_f32_e32 v115, 1.0, v115
	v_rcp_f32_e32 v112, v112
	v_rcp_f32_e32 v113, v113
	v_rcp_f32_e32 v114, v114
	v_rcp_f32_e32 v115, v115
	v_mul_f32_e32 v100, 0xbfb8aa3b, v100
	v_mul_f32_e32 v101, 0xbfb8aa3b, v101
	v_mul_f32_e32 v102, 0xbfb8aa3b, v102
	v_mul_f32_e32 v103, 0xbfb8aa3b, v103
	v_exp_f32_e32 v100, v100
	v_exp_f32_e32 v101, v101
	v_exp_f32_e32 v102, v102
	v_exp_f32_e32 v103, v103
	v_add_f32_e32 v100, 1.0, v100
	v_add_f32_e32 v101, 1.0, v101
	v_add_f32_e32 v102, 1.0, v102
	v_add_f32_e32 v103, 1.0, v103
	v_rcp_f32_e32 v100, v100
	v_rcp_f32_e32 v101, v101
	v_rcp_f32_e32 v102, v102
	v_rcp_f32_e32 v103, v103
	v_mul_f32_e32 v96, 0xbfb8aa3b, v96
	v_mul_f32_e32 v97, 0xbfb8aa3b, v97
	v_mul_f32_e32 v98, 0xbfb8aa3b, v98
	v_mul_f32_e32 v99, 0xbfb8aa3b, v99
	v_exp_f32_e32 v96, v96
	v_exp_f32_e32 v97, v97
	v_exp_f32_e32 v98, v98
	v_exp_f32_e32 v99, v99
	v_add_f32_e32 v96, 1.0, v96
	v_add_f32_e32 v97, 1.0, v97
	v_add_f32_e32 v98, 1.0, v98
	v_add_f32_e32 v99, 1.0, v99
	v_rcp_f32_e32 v96, v96
	v_rcp_f32_e32 v97, v97
	v_rcp_f32_e32 v98, v98
	v_rcp_f32_e32 v99, v99
	v_mul_f32_e32 v84, 0xbfb8aa3b, v84
	v_mul_f32_e32 v85, 0xbfb8aa3b, v85
	v_mul_f32_e32 v86, 0xbfb8aa3b, v86
	v_mul_f32_e32 v87, 0xbfb8aa3b, v87
	v_exp_f32_e32 v84, v84
	v_exp_f32_e32 v85, v85
	v_exp_f32_e32 v86, v86
	v_exp_f32_e32 v87, v87
	v_add_f32_e32 v84, 1.0, v84
	v_add_f32_e32 v85, 1.0, v85
	v_add_f32_e32 v86, 1.0, v86
	v_add_f32_e32 v87, 1.0, v87
	v_rcp_f32_e32 v84, v84
	v_rcp_f32_e32 v85, v85
	v_rcp_f32_e32 v86, v86
	v_rcp_f32_e32 v87, v87
	v_mul_f32_e32 v80, 0xbfb8aa3b, v80
	v_mul_f32_e32 v81, 0xbfb8aa3b, v81
	v_mul_f32_e32 v82, 0xbfb8aa3b, v82
	v_mul_f32_e32 v83, 0xbfb8aa3b, v83
	v_exp_f32_e32 v80, v80
	v_exp_f32_e32 v81, v81
	v_exp_f32_e32 v82, v82
	v_exp_f32_e32 v83, v83
	v_add_f32_e32 v80, 1.0, v80
	v_add_f32_e32 v81, 1.0, v81
	v_add_f32_e32 v82, 1.0, v82
	v_add_f32_e32 v83, 1.0, v83
	v_rcp_f32_e32 v80, v80
	v_rcp_f32_e32 v81, v81
	v_rcp_f32_e32 v82, v82
	v_rcp_f32_e32 v83, v83
	v_mul_f32_e32 v68, 0xbfb8aa3b, v68
	v_mul_f32_e32 v69, 0xbfb8aa3b, v69
	v_mul_f32_e32 v70, 0xbfb8aa3b, v70
	v_mul_f32_e32 v71, 0xbfb8aa3b, v71
	v_exp_f32_e32 v68, v68
	v_exp_f32_e32 v69, v69
	v_exp_f32_e32 v70, v70
	v_exp_f32_e32 v71, v71
	v_add_f32_e32 v68, 1.0, v68
	v_add_f32_e32 v69, 1.0, v69
	v_add_f32_e32 v70, 1.0, v70
	v_add_f32_e32 v71, 1.0, v71
	v_rcp_f32_e32 v68, v68
	v_rcp_f32_e32 v69, v69
	v_rcp_f32_e32 v70, v70
	v_rcp_f32_e32 v71, v71
	v_mul_f32_e32 v64, 0xbfb8aa3b, v64
	v_mul_f32_e32 v65, 0xbfb8aa3b, v65
	v_mul_f32_e32 v66, 0xbfb8aa3b, v66
	v_mul_f32_e32 v67, 0xbfb8aa3b, v67
	v_exp_f32_e32 v64, v64
	v_exp_f32_e32 v65, v65
	v_exp_f32_e32 v66, v66
	v_exp_f32_e32 v67, v67
	v_add_f32_e32 v64, 1.0, v64
	v_add_f32_e32 v65, 1.0, v65
	v_add_f32_e32 v66, 1.0, v66
	v_add_f32_e32 v67, 1.0, v67
	v_rcp_f32_e32 v64, v64
	v_rcp_f32_e32 v65, v65
	v_rcp_f32_e32 v66, v66
	v_rcp_f32_e32 v67, v67
	v_mul_f32_e32 v60, 0xbfb8aa3b, v60
	v_mul_f32_e32 v61, 0xbfb8aa3b, v61
	v_mul_f32_e32 v62, 0xbfb8aa3b, v62
	v_mul_f32_e32 v63, 0xbfb8aa3b, v63
	v_exp_f32_e32 v60, v60
	v_exp_f32_e32 v61, v61
	v_exp_f32_e32 v62, v62
	v_exp_f32_e32 v63, v63
	v_add_f32_e32 v60, 1.0, v60
	v_add_f32_e32 v61, 1.0, v61
	v_add_f32_e32 v62, 1.0, v62
	v_add_f32_e32 v63, 1.0, v63
	v_rcp_f32_e32 v60, v60
	v_rcp_f32_e32 v61, v61
	v_rcp_f32_e32 v62, v62
	v_rcp_f32_e32 v63, v63
	v_mul_f32_e32 v56, 0xbfb8aa3b, v56
	v_mul_f32_e32 v57, 0xbfb8aa3b, v57
	v_mul_f32_e32 v58, 0xbfb8aa3b, v58
	v_mul_f32_e32 v59, 0xbfb8aa3b, v59
	v_exp_f32_e32 v56, v56
	v_exp_f32_e32 v57, v57
	v_exp_f32_e32 v58, v58
	v_exp_f32_e32 v59, v59
	v_add_f32_e32 v56, 1.0, v56
	v_add_f32_e32 v57, 1.0, v57
	v_add_f32_e32 v58, 1.0, v58
	v_add_f32_e32 v59, 1.0, v59
	v_rcp_f32_e32 v56, v56
	v_rcp_f32_e32 v57, v57
	v_rcp_f32_e32 v58, v58
	v_rcp_f32_e32 v59, v59
	v_mul_f32_e32 v44, 0xbfb8aa3b, v44
	v_mul_f32_e32 v45, 0xbfb8aa3b, v45
	v_mul_f32_e32 v46, 0xbfb8aa3b, v46
	v_mul_f32_e32 v47, 0xbfb8aa3b, v47
	v_exp_f32_e32 v44, v44
	v_exp_f32_e32 v45, v45
	v_exp_f32_e32 v46, v46
	v_exp_f32_e32 v47, v47
	v_add_f32_e32 v44, 1.0, v44
	v_add_f32_e32 v45, 1.0, v45
	v_add_f32_e32 v46, 1.0, v46
	v_add_f32_e32 v47, 1.0, v47
	v_rcp_f32_e32 v44, v44
	v_rcp_f32_e32 v45, v45
	v_rcp_f32_e32 v46, v46
	v_rcp_f32_e32 v47, v47
	v_mul_f32_e32 v40, 0xbfb8aa3b, v40
	v_mul_f32_e32 v41, 0xbfb8aa3b, v41
	v_mul_f32_e32 v42, 0xbfb8aa3b, v42
	v_mul_f32_e32 v43, 0xbfb8aa3b, v43
	v_exp_f32_e32 v40, v40
	v_exp_f32_e32 v41, v41
	v_exp_f32_e32 v42, v42
	v_exp_f32_e32 v43, v43
	v_add_f32_e32 v40, 1.0, v40
	v_add_f32_e32 v41, 1.0, v41
	v_add_f32_e32 v42, 1.0, v42
	v_add_f32_e32 v43, 1.0, v43
	v_rcp_f32_e32 v40, v40
	v_rcp_f32_e32 v41, v41
	v_rcp_f32_e32 v42, v42
	v_rcp_f32_e32 v43, v43
	v_mul_f32_e32 v28, 0xbfb8aa3b, v28
	v_mul_f32_e32 v29, 0xbfb8aa3b, v29
	v_mul_f32_e32 v30, 0xbfb8aa3b, v30
	v_mul_f32_e32 v31, 0xbfb8aa3b, v31
	v_exp_f32_e32 v28, v28
	v_exp_f32_e32 v29, v29
	v_exp_f32_e32 v30, v30
	v_exp_f32_e32 v31, v31
	v_add_f32_e32 v28, 1.0, v28
	v_add_f32_e32 v29, 1.0, v29
	v_add_f32_e32 v30, 1.0, v30
	v_add_f32_e32 v31, 1.0, v31
	v_rcp_f32_e32 v28, v28
	v_rcp_f32_e32 v29, v29
	v_rcp_f32_e32 v30, v30
	v_rcp_f32_e32 v31, v31
	v_mul_f32_e32 v24, 0xbfb8aa3b, v24
	v_mul_f32_e32 v25, 0xbfb8aa3b, v25
	v_mul_f32_e32 v26, 0xbfb8aa3b, v26
	v_mul_f32_e32 v27, 0xbfb8aa3b, v27
	v_exp_f32_e32 v24, v24
	v_exp_f32_e32 v25, v25
	v_exp_f32_e32 v26, v26
	v_exp_f32_e32 v27, v27
	v_add_f32_e32 v24, 1.0, v24
	v_add_f32_e32 v25, 1.0, v25
	v_add_f32_e32 v26, 1.0, v26
	v_add_f32_e32 v27, 1.0, v27
	v_rcp_f32_e32 v24, v24
	v_rcp_f32_e32 v25, v25
	v_rcp_f32_e32 v26, v26
	v_rcp_f32_e32 v27, v27
	v_mul_f32_e32 v12, 0xbfb8aa3b, v12
	v_mul_f32_e32 v13, 0xbfb8aa3b, v13
	v_mul_f32_e32 v14, 0xbfb8aa3b, v14
	v_mul_f32_e32 v15, 0xbfb8aa3b, v15
	v_exp_f32_e32 v12, v12
	v_exp_f32_e32 v13, v13
	v_exp_f32_e32 v14, v14
	v_exp_f32_e32 v15, v15
	v_add_f32_e32 v12, 1.0, v12
	v_add_f32_e32 v13, 1.0, v13
	v_add_f32_e32 v14, 1.0, v14
	v_add_f32_e32 v15, 1.0, v15
	v_rcp_f32_e32 v12, v12
	v_rcp_f32_e32 v13, v13
	v_rcp_f32_e32 v14, v14
	v_rcp_f32_e32 v15, v15
	v_mul_f32_e32 v8, 0xbfb8aa3b, v8
	v_mul_f32_e32 v9, 0xbfb8aa3b, v9
	v_mul_f32_e32 v10, 0xbfb8aa3b, v10
	v_mul_f32_e32 v11, 0xbfb8aa3b, v11
	v_exp_f32_e32 v8, v8
	v_exp_f32_e32 v9, v9
	v_exp_f32_e32 v10, v10
	v_exp_f32_e32 v11, v11
	v_add_f32_e32 v8, 1.0, v8
	v_add_f32_e32 v9, 1.0, v9
	v_add_f32_e32 v10, 1.0, v10
	v_add_f32_e32 v11, 1.0, v11
	v_rcp_f32_e32 v8, v8
	v_rcp_f32_e32 v9, v9
	v_rcp_f32_e32 v10, v10
	v_rcp_f32_e32 v11, v11
	v_mul_f32_e32 v52, 0xbfb8aa3b, v52
	v_mul_f32_e32 v53, 0xbfb8aa3b, v53
	v_mul_f32_e32 v54, 0xbfb8aa3b, v54
	v_mul_f32_e32 v55, 0xbfb8aa3b, v55
	v_exp_f32_e32 v52, v52
	v_exp_f32_e32 v53, v53
	v_exp_f32_e32 v54, v54
	v_exp_f32_e32 v55, v55
	v_add_f32_e32 v52, 1.0, v52
	v_add_f32_e32 v53, 1.0, v53
	v_add_f32_e32 v54, 1.0, v54
	v_add_f32_e32 v55, 1.0, v55
	v_rcp_f32_e32 v52, v52
	v_rcp_f32_e32 v53, v53
	v_rcp_f32_e32 v54, v54
	v_rcp_f32_e32 v55, v55
	v_mul_f32_e32 v48, 0xbfb8aa3b, v48
	v_mul_f32_e32 v49, 0xbfb8aa3b, v49
	v_mul_f32_e32 v50, 0xbfb8aa3b, v50
	v_mul_f32_e32 v51, 0xbfb8aa3b, v51
	v_exp_f32_e32 v48, v48
	v_exp_f32_e32 v49, v49
	v_exp_f32_e32 v50, v50
	v_exp_f32_e32 v51, v51
	v_add_f32_e32 v48, 1.0, v48
	v_add_f32_e32 v49, 1.0, v49
	v_add_f32_e32 v50, 1.0, v50
	v_add_f32_e32 v51, 1.0, v51
	v_rcp_f32_e32 v48, v48
	v_rcp_f32_e32 v49, v49
	v_rcp_f32_e32 v50, v50
	v_rcp_f32_e32 v51, v51
	v_mul_f32_e32 v36, 0xbfb8aa3b, v36
	v_mul_f32_e32 v37, 0xbfb8aa3b, v37
	v_mul_f32_e32 v38, 0xbfb8aa3b, v38
	v_mul_f32_e32 v39, 0xbfb8aa3b, v39
	v_exp_f32_e32 v36, v36
	v_exp_f32_e32 v37, v37
	v_exp_f32_e32 v38, v38
	v_exp_f32_e32 v39, v39
	v_add_f32_e32 v36, 1.0, v36
	v_add_f32_e32 v37, 1.0, v37
	v_add_f32_e32 v38, 1.0, v38
	v_add_f32_e32 v39, 1.0, v39
	v_rcp_f32_e32 v36, v36
	v_rcp_f32_e32 v37, v37
	v_rcp_f32_e32 v38, v38
	v_rcp_f32_e32 v39, v39
	v_mul_f32_e32 v32, 0xbfb8aa3b, v32
	v_mul_f32_e32 v33, 0xbfb8aa3b, v33
	v_mul_f32_e32 v34, 0xbfb8aa3b, v34
	v_mul_f32_e32 v35, 0xbfb8aa3b, v35
	v_exp_f32_e32 v32, v32
	v_exp_f32_e32 v33, v33
	v_exp_f32_e32 v34, v34
	v_exp_f32_e32 v35, v35
	v_add_f32_e32 v32, 1.0, v32
	v_add_f32_e32 v33, 1.0, v33
	v_add_f32_e32 v34, 1.0, v34
	v_add_f32_e32 v35, 1.0, v35
	v_rcp_f32_e32 v32, v32
	v_rcp_f32_e32 v33, v33
	v_rcp_f32_e32 v34, v34
	v_rcp_f32_e32 v35, v35
	v_mul_f32_e32 v20, 0xbfb8aa3b, v20
	v_mul_f32_e32 v21, 0xbfb8aa3b, v21
	v_mul_f32_e32 v22, 0xbfb8aa3b, v22
	v_mul_f32_e32 v23, 0xbfb8aa3b, v23
	v_exp_f32_e32 v20, v20
	v_exp_f32_e32 v21, v21
	v_exp_f32_e32 v22, v22
	v_exp_f32_e32 v23, v23
	v_add_f32_e32 v20, 1.0, v20
	v_add_f32_e32 v21, 1.0, v21
	v_add_f32_e32 v22, 1.0, v22
	v_add_f32_e32 v23, 1.0, v23
	v_rcp_f32_e32 v20, v20
	v_rcp_f32_e32 v21, v21
	v_rcp_f32_e32 v22, v22
	v_rcp_f32_e32 v23, v23
	v_mul_f32_e32 v16, 0xbfb8aa3b, v16
	v_mul_f32_e32 v17, 0xbfb8aa3b, v17
	v_mul_f32_e32 v18, 0xbfb8aa3b, v18
	v_mul_f32_e32 v19, 0xbfb8aa3b, v19
	v_exp_f32_e32 v16, v16
	v_exp_f32_e32 v17, v17
	v_exp_f32_e32 v18, v18
	v_exp_f32_e32 v19, v19
	v_add_f32_e32 v16, 1.0, v16
	v_add_f32_e32 v17, 1.0, v17
	v_add_f32_e32 v18, 1.0, v18
	v_add_f32_e32 v19, 1.0, v19
	v_rcp_f32_e32 v16, v16
	v_rcp_f32_e32 v17, v17
	v_rcp_f32_e32 v18, v18
	v_rcp_f32_e32 v19, v19
	v_mul_f32_e32 v4, 0xbfb8aa3b, v4
	v_mul_f32_e32 v5, 0xbfb8aa3b, v5
	v_mul_f32_e32 v6, 0xbfb8aa3b, v6
	v_mul_f32_e32 v7, 0xbfb8aa3b, v7
	v_exp_f32_e32 v4, v4
	v_exp_f32_e32 v5, v5
	v_exp_f32_e32 v6, v6
	v_exp_f32_e32 v7, v7
	v_add_f32_e32 v4, 1.0, v4
	v_add_f32_e32 v5, 1.0, v5
	v_add_f32_e32 v6, 1.0, v6
	v_add_f32_e32 v7, 1.0, v7
	v_rcp_f32_e32 v4, v4
	v_rcp_f32_e32 v5, v5
	v_rcp_f32_e32 v6, v6
	v_rcp_f32_e32 v7, v7
	v_mul_f32_e32 v0, 0xbfb8aa3b, v0
	v_mul_f32_e32 v1, 0xbfb8aa3b, v1
	v_mul_f32_e32 v2, 0xbfb8aa3b, v2
	v_mul_f32_e32 v3, 0xbfb8aa3b, v3
	v_exp_f32_e32 v0, v0
	v_exp_f32_e32 v1, v1
	v_exp_f32_e32 v2, v2
	v_exp_f32_e32 v3, v3
	v_add_f32_e32 v0, 1.0, v0
	v_add_f32_e32 v1, 1.0, v1
	v_add_f32_e32 v2, 1.0, v2
	v_add_f32_e32 v3, 1.0, v3
	v_rcp_f32_e32 v0, v0
	v_rcp_f32_e32 v1, v1
	v_rcp_f32_e32 v2, v2
	v_rcp_f32_e32 v3, v3
	s_waitcnt vmcnt(15)
	v_permlane16_swap_b32 v148, v150
	v_permlane16_swap_b32 v149, v151
	v_lshlrev_b32_e32 v228, 16, v148
	v_and_b32_e32 v229, 0xffff0000, v148
	v_lshlrev_b32_e32 v230, 16, v149
	v_and_b32_e32 v231, 0xffff0000, v149
	v_pk_mul_f32 v[124:125], v[124:125], v[228:229]
	v_pk_mul_f32 v[126:127], v[126:127], v[230:231]
	v_lshlrev_b32_e32 v228, 16, v150
	v_and_b32_e32 v229, 0xffff0000, v150
	v_lshlrev_b32_e32 v230, 16, v151
	v_and_b32_e32 v231, 0xffff0000, v151
	v_pk_mul_f32 v[120:121], v[120:121], v[228:229]
	v_pk_mul_f32 v[122:123], v[122:123], v[230:231]
	v_cvt_pk_bf16_f32 v232, v124, v125
	v_cvt_pk_bf16_f32 v233, v126, v127
	v_cvt_pk_bf16_f32 v234, v120, v121
	v_cvt_pk_bf16_f32 v235, v122, v123
	s_nop 1
	v_permlane16_swap_b32 v232, v234
	v_permlane16_swap_b32 v233, v235
	global_store_dwordx4 v220, v[232:235], s[14:15] offset:0
	s_waitcnt vmcnt(15)
	v_permlane16_swap_b32 v152, v154
	v_permlane16_swap_b32 v153, v155
	v_lshlrev_b32_e32 v228, 16, v152
	v_and_b32_e32 v229, 0xffff0000, v152
	v_lshlrev_b32_e32 v230, 16, v153
	v_and_b32_e32 v231, 0xffff0000, v153
	v_pk_mul_f32 v[116:117], v[116:117], v[228:229]
	v_pk_mul_f32 v[118:119], v[118:119], v[230:231]
	v_lshlrev_b32_e32 v228, 16, v154
	v_and_b32_e32 v229, 0xffff0000, v154
	v_lshlrev_b32_e32 v230, 16, v155
	v_and_b32_e32 v231, 0xffff0000, v155
	v_pk_mul_f32 v[112:113], v[112:113], v[228:229]
	v_pk_mul_f32 v[114:115], v[114:115], v[230:231]
	v_cvt_pk_bf16_f32 v236, v116, v117
	v_cvt_pk_bf16_f32 v237, v118, v119
	v_cvt_pk_bf16_f32 v238, v112, v113
	v_cvt_pk_bf16_f32 v239, v114, v115
	s_nop 1
	v_permlane16_swap_b32 v236, v238
	v_permlane16_swap_b32 v237, v239
	global_store_dwordx4 v220, v[236:239], s[14:15] offset:256
	s_waitcnt vmcnt(15)
	v_permlane16_swap_b32 v156, v158
	v_permlane16_swap_b32 v157, v159
	v_lshlrev_b32_e32 v228, 16, v156
	v_and_b32_e32 v229, 0xffff0000, v156
	v_lshlrev_b32_e32 v230, 16, v157
	v_and_b32_e32 v231, 0xffff0000, v157
	v_pk_mul_f32 v[108:109], v[108:109], v[228:229]
	v_pk_mul_f32 v[110:111], v[110:111], v[230:231]
	v_lshlrev_b32_e32 v228, 16, v158
	v_and_b32_e32 v229, 0xffff0000, v158
	v_lshlrev_b32_e32 v230, 16, v159
	v_and_b32_e32 v231, 0xffff0000, v159
	v_pk_mul_f32 v[104:105], v[104:105], v[228:229]
	v_pk_mul_f32 v[106:107], v[106:107], v[230:231]
	v_cvt_pk_bf16_f32 v244, v108, v109
	v_cvt_pk_bf16_f32 v245, v110, v111
	v_cvt_pk_bf16_f32 v246, v104, v105
	v_cvt_pk_bf16_f32 v247, v106, v107
	s_nop 1
	v_permlane16_swap_b32 v244, v246
	v_permlane16_swap_b32 v245, v247
	global_store_dwordx4 v221, v[244:247], s[14:15] offset:0
	s_waitcnt vmcnt(15)
	v_permlane16_swap_b32 v160, v162
	v_permlane16_swap_b32 v161, v163
	v_lshlrev_b32_e32 v228, 16, v160
	v_and_b32_e32 v229, 0xffff0000, v160
	v_lshlrev_b32_e32 v230, 16, v161
	v_and_b32_e32 v231, 0xffff0000, v161
	v_pk_mul_f32 v[100:101], v[100:101], v[228:229]
	v_pk_mul_f32 v[102:103], v[102:103], v[230:231]
	v_lshlrev_b32_e32 v228, 16, v162
	v_and_b32_e32 v229, 0xffff0000, v162
	v_lshlrev_b32_e32 v230, 16, v163
	v_and_b32_e32 v231, 0xffff0000, v163
	v_pk_mul_f32 v[96:97], v[96:97], v[228:229]
	v_pk_mul_f32 v[98:99], v[98:99], v[230:231]
	v_cvt_pk_bf16_f32 v248, v100, v101
	v_cvt_pk_bf16_f32 v249, v102, v103
	v_cvt_pk_bf16_f32 v250, v96, v97
	v_cvt_pk_bf16_f32 v251, v98, v99
	s_nop 1
	v_permlane16_swap_b32 v248, v250
	v_permlane16_swap_b32 v249, v251
	global_store_dwordx4 v221, v[248:251], s[14:15] offset:256
	s_waitcnt vmcnt(15)
	v_permlane16_swap_b32 v164, v166
	v_permlane16_swap_b32 v165, v167
	v_lshlrev_b32_e32 v228, 16, v164
	v_and_b32_e32 v229, 0xffff0000, v164
	v_lshlrev_b32_e32 v230, 16, v165
	v_and_b32_e32 v231, 0xffff0000, v165
	v_pk_mul_f32 v[92:93], v[92:93], v[228:229]
	v_pk_mul_f32 v[94:95], v[94:95], v[230:231]
	v_lshlrev_b32_e32 v228, 16, v166
	v_and_b32_e32 v229, 0xffff0000, v166
	v_lshlrev_b32_e32 v230, 16, v167
	v_and_b32_e32 v231, 0xffff0000, v167
	v_pk_mul_f32 v[88:89], v[88:89], v[228:229]
	v_pk_mul_f32 v[90:91], v[90:91], v[230:231]
	v_cvt_pk_bf16_f32 v232, v92, v93
	v_cvt_pk_bf16_f32 v233, v94, v95
	v_cvt_pk_bf16_f32 v234, v88, v89
	v_cvt_pk_bf16_f32 v235, v90, v91
	s_nop 1
	v_permlane16_swap_b32 v232, v234
	v_permlane16_swap_b32 v233, v235
	global_store_dwordx4 v222, v[232:235], s[14:15] offset:0
	s_waitcnt vmcnt(15)
	v_permlane16_swap_b32 v168, v170
	v_permlane16_swap_b32 v169, v171
	v_lshlrev_b32_e32 v228, 16, v168
	v_and_b32_e32 v229, 0xffff0000, v168
	v_lshlrev_b32_e32 v230, 16, v169
	v_and_b32_e32 v231, 0xffff0000, v169
	v_pk_mul_f32 v[84:85], v[84:85], v[228:229]
	v_pk_mul_f32 v[86:87], v[86:87], v[230:231]
	v_lshlrev_b32_e32 v228, 16, v170
	v_and_b32_e32 v229, 0xffff0000, v170
	v_lshlrev_b32_e32 v230, 16, v171
	v_and_b32_e32 v231, 0xffff0000, v171
	v_pk_mul_f32 v[80:81], v[80:81], v[228:229]
	v_pk_mul_f32 v[82:83], v[82:83], v[230:231]
	v_cvt_pk_bf16_f32 v236, v84, v85
	v_cvt_pk_bf16_f32 v237, v86, v87
	v_cvt_pk_bf16_f32 v238, v80, v81
	v_cvt_pk_bf16_f32 v239, v82, v83
	s_nop 1
	v_permlane16_swap_b32 v236, v238
	v_permlane16_swap_b32 v237, v239
	global_store_dwordx4 v222, v[236:239], s[14:15] offset:256
	s_waitcnt vmcnt(15)
	v_permlane16_swap_b32 v172, v174
	v_permlane16_swap_b32 v173, v175
	v_lshlrev_b32_e32 v228, 16, v172
	v_and_b32_e32 v229, 0xffff0000, v172
	v_lshlrev_b32_e32 v230, 16, v173
	v_and_b32_e32 v231, 0xffff0000, v173
	v_pk_mul_f32 v[76:77], v[76:77], v[228:229]
	v_pk_mul_f32 v[78:79], v[78:79], v[230:231]
	v_lshlrev_b32_e32 v228, 16, v174
	v_and_b32_e32 v229, 0xffff0000, v174
	v_lshlrev_b32_e32 v230, 16, v175
	v_and_b32_e32 v231, 0xffff0000, v175
	v_pk_mul_f32 v[72:73], v[72:73], v[228:229]
	v_pk_mul_f32 v[74:75], v[74:75], v[230:231]
	v_cvt_pk_bf16_f32 v244, v76, v77
	v_cvt_pk_bf16_f32 v245, v78, v79
	v_cvt_pk_bf16_f32 v246, v72, v73
	v_cvt_pk_bf16_f32 v247, v74, v75
	s_nop 1
	v_permlane16_swap_b32 v244, v246
	v_permlane16_swap_b32 v245, v247
	global_store_dwordx4 v223, v[244:247], s[14:15] offset:0
	s_waitcnt vmcnt(15)
	v_permlane16_swap_b32 v176, v178
	v_permlane16_swap_b32 v177, v179
	v_lshlrev_b32_e32 v228, 16, v176
	v_and_b32_e32 v229, 0xffff0000, v176
	v_lshlrev_b32_e32 v230, 16, v177
	v_and_b32_e32 v231, 0xffff0000, v177
	v_pk_mul_f32 v[68:69], v[68:69], v[228:229]
	v_pk_mul_f32 v[70:71], v[70:71], v[230:231]
	v_lshlrev_b32_e32 v228, 16, v178
	v_and_b32_e32 v229, 0xffff0000, v178
	v_lshlrev_b32_e32 v230, 16, v179
	v_and_b32_e32 v231, 0xffff0000, v179
	v_pk_mul_f32 v[64:65], v[64:65], v[228:229]
	v_pk_mul_f32 v[66:67], v[66:67], v[230:231]
	v_cvt_pk_bf16_f32 v248, v68, v69
	v_cvt_pk_bf16_f32 v249, v70, v71
	v_cvt_pk_bf16_f32 v250, v64, v65
	v_cvt_pk_bf16_f32 v251, v66, v67
	s_nop 1
	v_permlane16_swap_b32 v248, v250
	v_permlane16_swap_b32 v249, v251
	global_store_dwordx4 v223, v[248:251], s[14:15] offset:256
	s_waitcnt vmcnt(15)
	v_permlane16_swap_b32 v180, v182
	v_permlane16_swap_b32 v181, v183
	v_lshlrev_b32_e32 v228, 16, v180
	v_and_b32_e32 v229, 0xffff0000, v180
	v_lshlrev_b32_e32 v230, 16, v181
	v_and_b32_e32 v231, 0xffff0000, v181
	v_pk_mul_f32 v[60:61], v[60:61], v[228:229]
	v_pk_mul_f32 v[62:63], v[62:63], v[230:231]
	v_lshlrev_b32_e32 v228, 16, v182
	v_and_b32_e32 v229, 0xffff0000, v182
	v_lshlrev_b32_e32 v230, 16, v183
	v_and_b32_e32 v231, 0xffff0000, v183
	v_pk_mul_f32 v[56:57], v[56:57], v[228:229]
	v_pk_mul_f32 v[58:59], v[58:59], v[230:231]
	v_cvt_pk_bf16_f32 v232, v60, v61
	v_cvt_pk_bf16_f32 v233, v62, v63
	v_cvt_pk_bf16_f32 v234, v56, v57
	v_cvt_pk_bf16_f32 v235, v58, v59
	s_nop 1
	v_permlane16_swap_b32 v232, v234
	v_permlane16_swap_b32 v233, v235
	global_store_dwordx4 v224, v[232:235], s[14:15] offset:0
	s_waitcnt vmcnt(15)
	v_permlane16_swap_b32 v184, v186
	v_permlane16_swap_b32 v185, v187
	v_lshlrev_b32_e32 v228, 16, v184
	v_and_b32_e32 v229, 0xffff0000, v184
	v_lshlrev_b32_e32 v230, 16, v185
	v_and_b32_e32 v231, 0xffff0000, v185
	v_pk_mul_f32 v[52:53], v[52:53], v[228:229]
	v_pk_mul_f32 v[54:55], v[54:55], v[230:231]
	v_lshlrev_b32_e32 v228, 16, v186
	v_and_b32_e32 v229, 0xffff0000, v186
	v_lshlrev_b32_e32 v230, 16, v187
	v_and_b32_e32 v231, 0xffff0000, v187
	v_pk_mul_f32 v[48:49], v[48:49], v[228:229]
	v_pk_mul_f32 v[50:51], v[50:51], v[230:231]
	v_cvt_pk_bf16_f32 v236, v52, v53
	v_cvt_pk_bf16_f32 v237, v54, v55
	v_cvt_pk_bf16_f32 v238, v48, v49
	v_cvt_pk_bf16_f32 v239, v50, v51
	s_nop 1
	v_permlane16_swap_b32 v236, v238
	v_permlane16_swap_b32 v237, v239
	global_store_dwordx4 v224, v[236:239], s[14:15] offset:256
	s_waitcnt vmcnt(15)
	v_permlane16_swap_b32 v188, v190
	v_permlane16_swap_b32 v189, v191
	v_lshlrev_b32_e32 v228, 16, v188
	v_and_b32_e32 v229, 0xffff0000, v188
	v_lshlrev_b32_e32 v230, 16, v189
	v_and_b32_e32 v231, 0xffff0000, v189
	v_pk_mul_f32 v[44:45], v[44:45], v[228:229]
	v_pk_mul_f32 v[46:47], v[46:47], v[230:231]
	v_lshlrev_b32_e32 v228, 16, v190
	v_and_b32_e32 v229, 0xffff0000, v190
	v_lshlrev_b32_e32 v230, 16, v191
	v_and_b32_e32 v231, 0xffff0000, v191
	v_pk_mul_f32 v[40:41], v[40:41], v[228:229]
	v_pk_mul_f32 v[42:43], v[42:43], v[230:231]
	v_cvt_pk_bf16_f32 v244, v44, v45
	v_cvt_pk_bf16_f32 v245, v46, v47
	v_cvt_pk_bf16_f32 v246, v40, v41
	v_cvt_pk_bf16_f32 v247, v42, v43
	s_nop 1
	v_permlane16_swap_b32 v244, v246
	v_permlane16_swap_b32 v245, v247
	global_store_dwordx4 v225, v[244:247], s[14:15] offset:0
	s_waitcnt vmcnt(15)
	v_permlane16_swap_b32 v192, v194
	v_permlane16_swap_b32 v193, v195
	v_lshlrev_b32_e32 v228, 16, v192
	v_and_b32_e32 v229, 0xffff0000, v192
	v_lshlrev_b32_e32 v230, 16, v193
	v_and_b32_e32 v231, 0xffff0000, v193
	v_pk_mul_f32 v[36:37], v[36:37], v[228:229]
	v_pk_mul_f32 v[38:39], v[38:39], v[230:231]
	v_lshlrev_b32_e32 v228, 16, v194
	v_and_b32_e32 v229, 0xffff0000, v194
	v_lshlrev_b32_e32 v230, 16, v195
	v_and_b32_e32 v231, 0xffff0000, v195
	v_pk_mul_f32 v[32:33], v[32:33], v[228:229]
	v_pk_mul_f32 v[34:35], v[34:35], v[230:231]
	v_cvt_pk_bf16_f32 v248, v36, v37
	v_cvt_pk_bf16_f32 v249, v38, v39
	v_cvt_pk_bf16_f32 v250, v32, v33
	v_cvt_pk_bf16_f32 v251, v34, v35
	s_nop 1
	v_permlane16_swap_b32 v248, v250
	v_permlane16_swap_b32 v249, v251
	global_store_dwordx4 v225, v[248:251], s[14:15] offset:256
	s_waitcnt vmcnt(15)
	v_permlane16_swap_b32 v196, v198
	v_permlane16_swap_b32 v197, v199
	v_lshlrev_b32_e32 v228, 16, v196
	v_and_b32_e32 v229, 0xffff0000, v196
	v_lshlrev_b32_e32 v230, 16, v197
	v_and_b32_e32 v231, 0xffff0000, v197
	v_pk_mul_f32 v[28:29], v[28:29], v[228:229]
	v_pk_mul_f32 v[30:31], v[30:31], v[230:231]
	v_lshlrev_b32_e32 v228, 16, v198
	v_and_b32_e32 v229, 0xffff0000, v198
	v_lshlrev_b32_e32 v230, 16, v199
	v_and_b32_e32 v231, 0xffff0000, v199
	v_pk_mul_f32 v[24:25], v[24:25], v[228:229]
	v_pk_mul_f32 v[26:27], v[26:27], v[230:231]
	v_cvt_pk_bf16_f32 v232, v28, v29
	v_cvt_pk_bf16_f32 v233, v30, v31
	v_cvt_pk_bf16_f32 v234, v24, v25
	v_cvt_pk_bf16_f32 v235, v26, v27
	s_nop 1
	v_permlane16_swap_b32 v232, v234
	v_permlane16_swap_b32 v233, v235
	global_store_dwordx4 v226, v[232:235], s[14:15] offset:0
	s_waitcnt vmcnt(15)
	v_permlane16_swap_b32 v200, v202
	v_permlane16_swap_b32 v201, v203
	v_lshlrev_b32_e32 v228, 16, v200
	v_and_b32_e32 v229, 0xffff0000, v200
	v_lshlrev_b32_e32 v230, 16, v201
	v_and_b32_e32 v231, 0xffff0000, v201
	v_pk_mul_f32 v[20:21], v[20:21], v[228:229]
	v_pk_mul_f32 v[22:23], v[22:23], v[230:231]
	v_lshlrev_b32_e32 v228, 16, v202
	v_and_b32_e32 v229, 0xffff0000, v202
	v_lshlrev_b32_e32 v230, 16, v203
	v_and_b32_e32 v231, 0xffff0000, v203
	v_pk_mul_f32 v[16:17], v[16:17], v[228:229]
	v_pk_mul_f32 v[18:19], v[18:19], v[230:231]
	v_cvt_pk_bf16_f32 v236, v20, v21
	v_cvt_pk_bf16_f32 v237, v22, v23
	v_cvt_pk_bf16_f32 v238, v16, v17
	v_cvt_pk_bf16_f32 v239, v18, v19
	s_nop 1
	v_permlane16_swap_b32 v236, v238
	v_permlane16_swap_b32 v237, v239
	global_store_dwordx4 v226, v[236:239], s[14:15] offset:256
	s_waitcnt vmcnt(15)
	v_permlane16_swap_b32 v204, v206
	v_permlane16_swap_b32 v205, v207
	v_lshlrev_b32_e32 v228, 16, v204
	v_and_b32_e32 v229, 0xffff0000, v204
	v_lshlrev_b32_e32 v230, 16, v205
	v_and_b32_e32 v231, 0xffff0000, v205
	v_pk_mul_f32 v[12:13], v[12:13], v[228:229]
	v_pk_mul_f32 v[14:15], v[14:15], v[230:231]
	v_lshlrev_b32_e32 v228, 16, v206
	v_and_b32_e32 v229, 0xffff0000, v206
	v_lshlrev_b32_e32 v230, 16, v207
	v_and_b32_e32 v231, 0xffff0000, v207
	v_pk_mul_f32 v[8:9], v[8:9], v[228:229]
	v_pk_mul_f32 v[10:11], v[10:11], v[230:231]
	v_cvt_pk_bf16_f32 v244, v12, v13
	v_cvt_pk_bf16_f32 v245, v14, v15
	v_cvt_pk_bf16_f32 v246, v8, v9
	v_cvt_pk_bf16_f32 v247, v10, v11
	s_nop 1
	v_permlane16_swap_b32 v244, v246
	v_permlane16_swap_b32 v245, v247
	global_store_dwordx4 v227, v[244:247], s[14:15] offset:0
	s_waitcnt vmcnt(15)
	v_permlane16_swap_b32 v208, v210
	v_permlane16_swap_b32 v209, v211
	v_lshlrev_b32_e32 v228, 16, v208
	v_and_b32_e32 v229, 0xffff0000, v208
	v_lshlrev_b32_e32 v230, 16, v209
	v_and_b32_e32 v231, 0xffff0000, v209
	v_pk_mul_f32 v[4:5], v[4:5], v[228:229]
	v_pk_mul_f32 v[6:7], v[6:7], v[230:231]
	v_lshlrev_b32_e32 v228, 16, v210
	v_and_b32_e32 v229, 0xffff0000, v210
	v_lshlrev_b32_e32 v230, 16, v211
	v_and_b32_e32 v231, 0xffff0000, v211
	v_pk_mul_f32 v[0:1], v[0:1], v[228:229]
	v_pk_mul_f32 v[2:3], v[2:3], v[230:231]
	v_cvt_pk_bf16_f32 v248, v4, v5
	v_cvt_pk_bf16_f32 v249, v6, v7
	v_cvt_pk_bf16_f32 v250, v0, v1
	v_cvt_pk_bf16_f32 v251, v2, v3
	s_nop 1
	v_permlane16_swap_b32 v248, v250
	v_permlane16_swap_b32 v249, v251
	global_store_dwordx4 v227, v[248:251], s[14:15] offset:256
	s_andn2_b64 vcc, exec, s[22:23]
	s_mov_b64 s[22:23], -1
	s_cbranch_vccnz .LBB0_1056
	s_andn2_b64 vcc, exec, s[10:11]
	s_cbranch_vccnz .LBB0_1055
	s_barrier
	s_branch .LBB0_1055
